# P10: workgroup s_barrier at the top of each token iteration (keeps the 8 waves = 8 consecutive tokens in step)
# speedup vs baseline: 1.0155x; 1.0011x over previous
; __device__ __forceinline__ float bf_lo(unsigned u) { return __uint_as_float(u << 16); }
; __device__ __forceinline__ float bf_hi(unsigned u) { return __uint_as_float(u & 0xffff0000u); }
; __global__ void __launch_bounds__(NT, 2) mk_fwd(Args args) {
;     ...
;         for (int tok = gw; tok < MTOK; tok += NGW) {
;             const int b = tok >> 11;
;             f32x2 hf2[16];
; #pragma unroll
;             for (int j = 0; j < 4; ++j) { const u32x4 a = *(const u32x4*)(HB + (size_t)tok * DM + lane * 32 + j * 8);
; #pragma unroll
;                 for (int q = 0; q < 4; ++q) hf2[j * 4 + q] = (f32x2){bf_lo(a[q]), bf_hi(a[q])}; }
;             const int e0 = EIDX[(size_t)tok * 128 + lane], e1 = EIDX[(size_t)tok * 128 + 64 + lane];
;             const float g0 = GATE[(size_t)tok * 128 + lane], g1 = GATE[(size_t)tok * 128 + 64 + lane];
;             const bool hi32 = (lane & 32) != 0, hi16 = (lane & 16) != 0; const int l3 = (lane & 3) << 4;
.LBB0_886:
	s_barrier
	s_ashr_i32 s71, s70, 31
	s_lshl_b64 s[4:5], s[70:71], 9
	v_lshl_or_b32 v0, v128, 2, s4
	v_mov_b32_e32 v1, s5
	v_lshl_add_u64 v[2:3], s[46:47], 0, v[0:1]
	global_load_dword v108, v[2:3], off
	s_lshl_b64 s[4:5], s[70:71], 12
	v_lshl_add_u64 v[2:3], v[96:97], 0, s[4:5]
	global_load_dwordx4 v[32:35], v[2:3], off offset:48
	global_load_dwordx4 v[36:39], v[2:3], off offset:32
	global_load_dwordx4 v[40:43], v[2:3], off offset:16
	global_load_dwordx4 v[44:47], v[2:3], off
	v_or_b32_e32 v2, 0x100, v0
	v_mov_b32_e32 v3, v1
	v_lshl_add_u64 v[0:1], s[48:49], 0, v[0:1]
	v_lshl_add_u64 v[4:5], s[46:47], 0, v[2:3]
	v_lshl_add_u64 v[2:3], s[48:49], 0, v[2:3]
	global_load_dword v106, v[4:5], off
	global_load_dword v110, v[0:1], off
	global_load_dword v156, v[2:3], off
	s_waitcnt vmcnt(0)
	v_lshl_or_b32 v170, v108, 7, v128
	v_lshlrev_b32_e32 v171, 7, v106
	v_or_b32_e32 v174, 64, v128
	v_or_b32_e32 v171, v171, v174
	s_nop 0
	s_xnor_b64 s[62:63], s[50:51], s[52:53]
	s_nop 1
	v_min_u32_dpp v172, v170, v170 quad_perm:[1,0,3,2] row_mask:0xf bank_mask:0xf
	v_max_u32_dpp v173, v170, v170 quad_perm:[1,0,3,2] row_mask:0xf bank_mask:0xf
	v_min_u32_dpp v175, v171, v171 quad_perm:[1,0,3,2] row_mask:0xf bank_mask:0xf
	v_max_u32_dpp v176, v171, v171 quad_perm:[1,0,3,2] row_mask:0xf bank_mask:0xf
	v_cndmask_b32_e64 v170, v173, v172, s[62:63]
	v_cndmask_b32_e64 v171, v176, v175, s[62:63]
	s_xnor_b64 s[62:63], s[52:53], s[54:55]
	s_nop 1
	v_min_u32_dpp v172, v170, v170 quad_perm:[2,3,0,1] row_mask:0xf bank_mask:0xf
	v_max_u32_dpp v173, v170, v170 quad_perm:[2,3,0,1] row_mask:0xf bank_mask:0xf
	v_min_u32_dpp v175, v171, v171 quad_perm:[2,3,0,1] row_mask:0xf bank_mask:0xf
	v_max_u32_dpp v176, v171, v171 quad_perm:[2,3,0,1] row_mask:0xf bank_mask:0xf
	v_cndmask_b32_e64 v170, v173, v172, s[62:63]
	v_cndmask_b32_e64 v171, v176, v175, s[62:63]
	s_xnor_b64 s[62:63], s[50:51], s[54:55]
	s_nop 1
	v_min_u32_dpp v172, v170, v170 quad_perm:[1,0,3,2] row_mask:0xf bank_mask:0xf
	v_max_u32_dpp v173, v170, v170 quad_perm:[1,0,3,2] row_mask:0xf bank_mask:0xf
	v_min_u32_dpp v175, v171, v171 quad_perm:[1,0,3,2] row_mask:0xf bank_mask:0xf
	v_max_u32_dpp v176, v171, v171 quad_perm:[1,0,3,2] row_mask:0xf bank_mask:0xf
	v_cndmask_b32_e64 v170, v173, v172, s[62:63]
	v_cndmask_b32_e64 v171, v176, v175, s[62:63]
	s_xnor_b64 s[62:63], s[54:55], s[56:57]
	s_nop 1
	v_mov_b32_dpp v174, v170 row_half_mirror row_mask:0xf bank_mask:0xf
	v_mov_b32_dpp v177, v171 row_half_mirror row_mask:0xf bank_mask:0xf
	s_nop 0
	v_min_u32_dpp v172, v174, v170 quad_perm:[3,2,1,0] row_mask:0xf bank_mask:0xf
	v_max_u32_dpp v173, v174, v170 quad_perm:[3,2,1,0] row_mask:0xf bank_mask:0xf
	v_min_u32_dpp v175, v177, v171 quad_perm:[3,2,1,0] row_mask:0xf bank_mask:0xf
	v_max_u32_dpp v176, v177, v171 quad_perm:[3,2,1,0] row_mask:0xf bank_mask:0xf
	v_cndmask_b32_e64 v170, v173, v172, s[62:63]
	v_cndmask_b32_e64 v171, v176, v175, s[62:63]
	s_xnor_b64 s[62:63], s[52:53], s[56:57]
	s_nop 1
	v_min_u32_dpp v172, v170, v170 quad_perm:[2,3,0,1] row_mask:0xf bank_mask:0xf
	v_max_u32_dpp v173, v170, v170 quad_perm:[2,3,0,1] row_mask:0xf bank_mask:0xf
	v_min_u32_dpp v175, v171, v171 quad_perm:[2,3,0,1] row_mask:0xf bank_mask:0xf
	v_max_u32_dpp v176, v171, v171 quad_perm:[2,3,0,1] row_mask:0xf bank_mask:0xf
	v_cndmask_b32_e64 v170, v173, v172, s[62:63]
	v_cndmask_b32_e64 v171, v176, v175, s[62:63]
	s_xnor_b64 s[62:63], s[50:51], s[56:57]
	s_nop 1
	v_min_u32_dpp v172, v170, v170 quad_perm:[1,0,3,2] row_mask:0xf bank_mask:0xf
	v_max_u32_dpp v173, v170, v170 quad_perm:[1,0,3,2] row_mask:0xf bank_mask:0xf
	v_min_u32_dpp v175, v171, v171 quad_perm:[1,0,3,2] row_mask:0xf bank_mask:0xf
	v_max_u32_dpp v176, v171, v171 quad_perm:[1,0,3,2] row_mask:0xf bank_mask:0xf
	v_cndmask_b32_e64 v170, v173, v172, s[62:63]
	v_cndmask_b32_e64 v171, v176, v175, s[62:63]
	s_xnor_b64 s[62:63], s[56:57], s[58:59]
	s_nop 1
	v_min_u32_dpp v172, v170, v170 row_ror:8 row_mask:0xf bank_mask:0xf
	v_max_u32_dpp v173, v170, v170 row_ror:8 row_mask:0xf bank_mask:0xf
	v_min_u32_dpp v175, v171, v171 row_ror:8 row_mask:0xf bank_mask:0xf
	v_max_u32_dpp v176, v171, v171 row_ror:8 row_mask:0xf bank_mask:0xf
	v_cndmask_b32_e64 v170, v173, v172, s[62:63]
	v_cndmask_b32_e64 v171, v176, v175, s[62:63]
	s_xnor_b64 s[62:63], s[54:55], s[58:59]
	s_nop 1
	v_mov_b32_dpp v174, v170 row_half_mirror row_mask:0xf bank_mask:0xf
	v_mov_b32_dpp v177, v171 row_half_mirror row_mask:0xf bank_mask:0xf
	s_nop 0
	v_min_u32_dpp v172, v174, v170 quad_perm:[3,2,1,0] row_mask:0xf bank_mask:0xf
	v_max_u32_dpp v173, v174, v170 quad_perm:[3,2,1,0] row_mask:0xf bank_mask:0xf
	v_min_u32_dpp v175, v177, v171 quad_perm:[3,2,1,0] row_mask:0xf bank_mask:0xf
	v_max_u32_dpp v176, v177, v171 quad_perm:[3,2,1,0] row_mask:0xf bank_mask:0xf
	v_cndmask_b32_e64 v170, v173, v172, s[62:63]
	v_cndmask_b32_e64 v171, v176, v175, s[62:63]
	s_xnor_b64 s[62:63], s[52:53], s[58:59]
	s_nop 1
	v_min_u32_dpp v172, v170, v170 quad_perm:[2,3,0,1] row_mask:0xf bank_mask:0xf
	v_max_u32_dpp v173, v170, v170 quad_perm:[2,3,0,1] row_mask:0xf bank_mask:0xf
	v_min_u32_dpp v175, v171, v171 quad_perm:[2,3,0,1] row_mask:0xf bank_mask:0xf
	v_max_u32_dpp v176, v171, v171 quad_perm:[2,3,0,1] row_mask:0xf bank_mask:0xf
	v_cndmask_b32_e64 v170, v173, v172, s[62:63]
	v_cndmask_b32_e64 v171, v176, v175, s[62:63]
	s_xnor_b64 s[62:63], s[50:51], s[58:59]
	s_nop 1
	v_min_u32_dpp v172, v170, v170 quad_perm:[1,0,3,2] row_mask:0xf bank_mask:0xf
	v_max_u32_dpp v173, v170, v170 quad_perm:[1,0,3,2] row_mask:0xf bank_mask:0xf
	v_min_u32_dpp v175, v171, v171 quad_perm:[1,0,3,2] row_mask:0xf bank_mask:0xf
	v_max_u32_dpp v176, v171, v171 quad_perm:[1,0,3,2] row_mask:0xf bank_mask:0xf
	v_cndmask_b32_e64 v170, v173, v172, s[62:63]
	v_cndmask_b32_e64 v171, v176, v175, s[62:63]
	s_xnor_b64 s[62:63], s[58:59], s[60:61]
	ds_bpermute_b32 v174, v146, v170
	ds_bpermute_b32 v177, v146, v171
	s_waitcnt lgkmcnt(1)
; __global__ void __launch_bounds__(NT, 2) mk_fwd(Args args) {
;     ...
;             const int e0 = EIDX[(size_t)tok * 128 + lane], e1 = EIDX[(size_t)tok * 128 + 64 + lane];
;             const float g0 = GATE[(size_t)tok * 128 + lane], g1 = GATE[(size_t)tok * 128 + 64 + lane];
	v_min_u32_e32 v172, v174, v170
	v_max_u32_e32 v173, v174, v170
	s_waitcnt lgkmcnt(0)
	v_min_u32_e32 v175, v177, v171
	v_max_u32_e32 v176, v177, v171
	v_cndmask_b32_e64 v170, v173, v172, s[62:63]
	v_cndmask_b32_e64 v171, v176, v175, s[62:63]
	s_xnor_b64 s[62:63], s[56:57], s[60:61]
	s_nop 1
	v_min_u32_dpp v172, v170, v170 row_ror:8 row_mask:0xf bank_mask:0xf
	v_max_u32_dpp v173, v170, v170 row_ror:8 row_mask:0xf bank_mask:0xf
	v_min_u32_dpp v175, v171, v171 row_ror:8 row_mask:0xf bank_mask:0xf
	v_max_u32_dpp v176, v171, v171 row_ror:8 row_mask:0xf bank_mask:0xf
	v_cndmask_b32_e64 v170, v173, v172, s[62:63]
	v_cndmask_b32_e64 v171, v176, v175, s[62:63]
	s_xnor_b64 s[62:63], s[54:55], s[60:61]
	s_nop 1
	v_mov_b32_dpp v174, v170 row_half_mirror row_mask:0xf bank_mask:0xf
	v_mov_b32_dpp v177, v171 row_half_mirror row_mask:0xf bank_mask:0xf
	s_nop 0
	v_min_u32_dpp v172, v174, v170 quad_perm:[3,2,1,0] row_mask:0xf bank_mask:0xf
	v_max_u32_dpp v173, v174, v170 quad_perm:[3,2,1,0] row_mask:0xf bank_mask:0xf
	v_min_u32_dpp v175, v177, v171 quad_perm:[3,2,1,0] row_mask:0xf bank_mask:0xf
	v_max_u32_dpp v176, v177, v171 quad_perm:[3,2,1,0] row_mask:0xf bank_mask:0xf
	v_cndmask_b32_e64 v170, v173, v172, s[62:63]
	v_cndmask_b32_e64 v171, v176, v175, s[62:63]
	s_xnor_b64 s[62:63], s[52:53], s[60:61]
	s_nop 1
	v_min_u32_dpp v172, v170, v170 quad_perm:[2,3,0,1] row_mask:0xf bank_mask:0xf
	v_max_u32_dpp v173, v170, v170 quad_perm:[2,3,0,1] row_mask:0xf bank_mask:0xf
	v_min_u32_dpp v175, v171, v171 quad_perm:[2,3,0,1] row_mask:0xf bank_mask:0xf
	v_max_u32_dpp v176, v171, v171 quad_perm:[2,3,0,1] row_mask:0xf bank_mask:0xf
	v_cndmask_b32_e64 v170, v173, v172, s[62:63]
	v_cndmask_b32_e64 v171, v176, v175, s[62:63]
	s_xnor_b64 s[62:63], s[50:51], s[60:61]
	s_nop 1
	v_min_u32_dpp v172, v170, v170 quad_perm:[1,0,3,2] row_mask:0xf bank_mask:0xf
	v_max_u32_dpp v173, v170, v170 quad_perm:[1,0,3,2] row_mask:0xf bank_mask:0xf
	v_min_u32_dpp v175, v171, v171 quad_perm:[1,0,3,2] row_mask:0xf bank_mask:0xf
	v_max_u32_dpp v176, v171, v171 quad_perm:[1,0,3,2] row_mask:0xf bank_mask:0xf
	v_cndmask_b32_e64 v170, v173, v172, s[62:63]
	v_cndmask_b32_e64 v171, v176, v175, s[62:63]
	ds_bpermute_b32 v174, v129, v170
	ds_bpermute_b32 v177, v129, v171
	s_waitcnt lgkmcnt(1)
	v_min_u32_e32 v172, v174, v170
	v_max_u32_e32 v173, v174, v170
	s_waitcnt lgkmcnt(0)
	v_min_u32_e32 v175, v177, v171
	v_max_u32_e32 v176, v177, v171
	v_cndmask_b32_e64 v170, v173, v172, s[60:61]
	v_cndmask_b32_e64 v171, v175, v176, s[60:61]
	ds_bpermute_b32 v174, v146, v170
	ds_bpermute_b32 v177, v146, v171
	s_waitcnt lgkmcnt(1)
	v_min_u32_e32 v172, v174, v170
	v_max_u32_e32 v173, v174, v170
	s_waitcnt lgkmcnt(0)
	v_min_u32_e32 v175, v177, v171
	v_max_u32_e32 v176, v177, v171
	v_cndmask_b32_e64 v170, v173, v172, s[58:59]
	v_cndmask_b32_e64 v171, v175, v176, s[58:59]
	s_nop 1
	v_min_u32_dpp v172, v170, v170 row_ror:8 row_mask:0xf bank_mask:0xf
	v_max_u32_dpp v173, v170, v170 row_ror:8 row_mask:0xf bank_mask:0xf
	v_min_u32_dpp v175, v171, v171 row_ror:8 row_mask:0xf bank_mask:0xf
	v_max_u32_dpp v176, v171, v171 row_ror:8 row_mask:0xf bank_mask:0xf
	v_cndmask_b32_e64 v170, v173, v172, s[56:57]
	v_cndmask_b32_e64 v171, v175, v176, s[56:57]
	s_nop 1
	v_mov_b32_dpp v174, v170 row_half_mirror row_mask:0xf bank_mask:0xf
	v_mov_b32_dpp v177, v171 row_half_mirror row_mask:0xf bank_mask:0xf
	s_nop 0
	v_min_u32_dpp v172, v174, v170 quad_perm:[3,2,1,0] row_mask:0xf bank_mask:0xf
	v_max_u32_dpp v173, v174, v170 quad_perm:[3,2,1,0] row_mask:0xf bank_mask:0xf
	v_min_u32_dpp v175, v177, v171 quad_perm:[3,2,1,0] row_mask:0xf bank_mask:0xf
	v_max_u32_dpp v176, v177, v171 quad_perm:[3,2,1,0] row_mask:0xf bank_mask:0xf
	v_cndmask_b32_e64 v170, v173, v172, s[54:55]
	v_cndmask_b32_e64 v171, v175, v176, s[54:55]
	s_nop 1
	v_min_u32_dpp v172, v170, v170 quad_perm:[2,3,0,1] row_mask:0xf bank_mask:0xf
	v_max_u32_dpp v173, v170, v170 quad_perm:[2,3,0,1] row_mask:0xf bank_mask:0xf
	v_min_u32_dpp v175, v171, v171 quad_perm:[2,3,0,1] row_mask:0xf bank_mask:0xf
	v_max_u32_dpp v176, v171, v171 quad_perm:[2,3,0,1] row_mask:0xf bank_mask:0xf
	v_cndmask_b32_e64 v170, v173, v172, s[52:53]
	v_cndmask_b32_e64 v171, v175, v176, s[52:53]
	s_nop 1
	v_min_u32_dpp v172, v170, v170 quad_perm:[1,0,3,2] row_mask:0xf bank_mask:0xf
	v_max_u32_dpp v173, v170, v170 quad_perm:[1,0,3,2] row_mask:0xf bank_mask:0xf
	v_min_u32_dpp v175, v171, v171 quad_perm:[1,0,3,2] row_mask:0xf bank_mask:0xf
	v_max_u32_dpp v176, v171, v171 quad_perm:[1,0,3,2] row_mask:0xf bank_mask:0xf
	v_cndmask_b32_e64 v170, v173, v172, s[50:51]
	v_cndmask_b32_e64 v171, v175, v176, s[50:51]
	v_min_u32_e32 v172, v170, v171
	v_max_u32_e32 v171, v170, v171
	v_mov_b32_e32 v170, v172
	ds_bpermute_b32 v174, v129, v170
	ds_bpermute_b32 v177, v129, v171
	s_waitcnt lgkmcnt(1)
	v_min_u32_e32 v172, v174, v170
	v_max_u32_e32 v173, v174, v170
	s_waitcnt lgkmcnt(0)
	v_min_u32_e32 v175, v177, v171
	v_max_u32_e32 v176, v177, v171
	v_cndmask_b32_e64 v170, v173, v172, s[60:61]
	v_cndmask_b32_e64 v171, v176, v175, s[60:61]
	ds_bpermute_b32 v174, v146, v170
	ds_bpermute_b32 v177, v146, v171
	s_waitcnt lgkmcnt(1)
	v_min_u32_e32 v172, v174, v170
	v_max_u32_e32 v173, v174, v170
	s_waitcnt lgkmcnt(0)
; __device__ __forceinline__ float bf_lo(unsigned u) { return __uint_as_float(u << 16); }
; __device__ __forceinline__ float bf_hi(unsigned u) { return __uint_as_float(u & 0xffff0000u); }
; #define PU_LOAD(BUF, EV, S0) do { _Pragma("unroll") for (int i = 0; i < 8; ++i) { const int row_ = __builtin_amdgcn_readlane(EV, (S0) + i); BUF[i & 3][i >> 2] = *(const u32x4*)(PU8 + (size_t)row_ * 1024 + lane * 16); } } while (0)
; __global__ void __launch_bounds__(NT, 2) mk_fwd(Args args) {
;     ...
;             f32x2 hf2[16];
; #pragma unroll
;             for (int j = 0; j < 4; ++j) { const u32x4 a = *(const u32x4*)(HB + (size_t)tok * DM + lane * 32 + j * 8);
; #pragma unroll
;                 for (int q = 0; q < 4; ++q) hf2[j * 4 + q] = (f32x2){bf_lo(a[q]), bf_hi(a[q])}; }
;             const int e0 = EIDX[(size_t)tok * 128 + lane], e1 = EIDX[(size_t)tok * 128 + 64 + lane];
;             const float g0 = GATE[(size_t)tok * 128 + lane], g1 = GATE[(size_t)tok * 128 + 64 + lane];
;             const bool hi32 = (lane & 32) != 0, hi16 = (lane & 16) != 0; const int l3 = (lane & 3) << 4;
;     ...
;             for (int hh = 0; hh < 2; ++hh) {
;                 const int ev = hh ? e1 : e0; const float gv = hh ? g1 : g0; float dv = 0.f;
;                 PU_LOAD(bA, ev, 0);
	v_min_u32_e32 v175, v177, v171
	v_max_u32_e32 v176, v177, v171
	v_cndmask_b32_e64 v170, v173, v172, s[58:59]
	v_cndmask_b32_e64 v171, v176, v175, s[58:59]
	s_nop 1
	v_min_u32_dpp v172, v170, v170 row_ror:8 row_mask:0xf bank_mask:0xf
	v_max_u32_dpp v173, v170, v170 row_ror:8 row_mask:0xf bank_mask:0xf
	v_min_u32_dpp v175, v171, v171 row_ror:8 row_mask:0xf bank_mask:0xf
	v_max_u32_dpp v176, v171, v171 row_ror:8 row_mask:0xf bank_mask:0xf
	v_cndmask_b32_e64 v170, v173, v172, s[56:57]
	v_cndmask_b32_e64 v171, v176, v175, s[56:57]
	s_nop 1
	v_mov_b32_dpp v174, v170 row_half_mirror row_mask:0xf bank_mask:0xf
	v_mov_b32_dpp v177, v171 row_half_mirror row_mask:0xf bank_mask:0xf
	s_nop 0
	v_min_u32_dpp v172, v174, v170 quad_perm:[3,2,1,0] row_mask:0xf bank_mask:0xf
	v_max_u32_dpp v173, v174, v170 quad_perm:[3,2,1,0] row_mask:0xf bank_mask:0xf
	v_min_u32_dpp v175, v177, v171 quad_perm:[3,2,1,0] row_mask:0xf bank_mask:0xf
	v_max_u32_dpp v176, v177, v171 quad_perm:[3,2,1,0] row_mask:0xf bank_mask:0xf
	v_cndmask_b32_e64 v170, v173, v172, s[54:55]
	v_cndmask_b32_e64 v171, v176, v175, s[54:55]
	s_nop 1
	v_min_u32_dpp v172, v170, v170 quad_perm:[2,3,0,1] row_mask:0xf bank_mask:0xf
	v_max_u32_dpp v173, v170, v170 quad_perm:[2,3,0,1] row_mask:0xf bank_mask:0xf
	v_min_u32_dpp v175, v171, v171 quad_perm:[2,3,0,1] row_mask:0xf bank_mask:0xf
	v_max_u32_dpp v176, v171, v171 quad_perm:[2,3,0,1] row_mask:0xf bank_mask:0xf
	v_cndmask_b32_e64 v170, v173, v172, s[52:53]
	v_cndmask_b32_e64 v171, v176, v175, s[52:53]
	s_nop 1
	v_min_u32_dpp v172, v170, v170 quad_perm:[1,0,3,2] row_mask:0xf bank_mask:0xf
	v_max_u32_dpp v173, v170, v170 quad_perm:[1,0,3,2] row_mask:0xf bank_mask:0xf
	v_min_u32_dpp v175, v171, v171 quad_perm:[1,0,3,2] row_mask:0xf bank_mask:0xf
	v_max_u32_dpp v176, v171, v171 quad_perm:[1,0,3,2] row_mask:0xf bank_mask:0xf
	v_cndmask_b32_e64 v170, v173, v172, s[50:51]
	v_cndmask_b32_e64 v171, v176, v175, s[50:51]
	v_and_b32_e32 v172, 63, v170
	v_lshlrev_b32_e32 v172, 2, v172
	ds_bpermute_b32 v173, v172, v110
	ds_bpermute_b32 v174, v172, v156
	v_and_b32_e32 v175, 63, v171
	v_lshlrev_b32_e32 v175, 2, v175
	ds_bpermute_b32 v176, v175, v110
	ds_bpermute_b32 v177, v175, v156
	v_and_b32_e32 v172, 64, v170
	v_cmp_eq_u32_e32 vcc, 0, v172
	s_waitcnt lgkmcnt(2)
	v_lshrrev_b32_e32 v108, 7, v170
	v_cndmask_b32_e32 v178, v174, v173, vcc
	v_and_b32_e32 v175, 64, v171
	v_cmp_eq_u32_e32 vcc, 0, v175
	s_waitcnt lgkmcnt(0)
	v_lshrrev_b32_e32 v106, 7, v171
	v_cndmask_b32_e32 v179, v177, v176, vcc
	v_mov_b32_e32 v110, v178
	v_mov_b32_e32 v156, v179
	s_mov_b32 s10, 0
	v_mov_b32_e32 v107, 0
	s_waitcnt vmcnt(6)
	v_lshlrev_b32_e32 v88, 16, v32
	v_readlane_b32 s4, v108, 0
	v_readlane_b32 s30, v108, 1
	v_readlane_b32 s34, v108, 2
	v_readlane_b32 s36, v108, 3
	v_readlane_b32 s38, v108, 4
	v_readlane_b32 s40, v108, 5
	v_readlane_b32 s42, v108, 6
	v_readlane_b32 s44, v108, 7
	s_ashr_i32 s5, s4, 31
	s_ashr_i32 s31, s30, 31
	s_ashr_i32 s35, s34, 31
	s_ashr_i32 s37, s36, 31
	s_ashr_i32 s39, s38, 31
	s_ashr_i32 s41, s40, 31
	s_ashr_i32 s43, s42, 31
	s_ashr_i32 s45, s44, 31
	s_lshl_b64 s[4:5], s[4:5], 10
	s_lshl_b64 s[30:31], s[30:31], 10
	s_lshl_b64 s[34:35], s[34:35], 10
	s_lshl_b64 s[36:37], s[36:37], 10
	s_lshl_b64 s[38:39], s[38:39], 10
	s_lshl_b64 s[40:41], s[40:41], 10
	s_lshl_b64 s[42:43], s[42:43], 10
	s_lshl_b64 s[44:45], s[44:45], 10
	v_lshl_add_u64 v[48:49], v[98:99], 0, s[4:5]
	v_lshl_add_u64 v[50:51], v[98:99], 0, s[30:31]
	v_lshl_add_u64 v[52:53], v[98:99], 0, s[34:35]
	v_lshl_add_u64 v[54:55], v[98:99], 0, s[36:37]
	v_lshl_add_u64 v[56:57], v[98:99], 0, s[38:39]
	v_lshl_add_u64 v[58:59], v[98:99], 0, s[40:41]
	v_lshl_add_u64 v[60:61], v[98:99], 0, s[42:43]
	v_lshl_add_u64 v[62:63], v[98:99], 0, s[44:45]
	global_load_dwordx4 v[0:3], v[48:49], off
	global_load_dwordx4 v[4:7], v[50:51], off
	global_load_dwordx4 v[8:11], v[52:53], off
	global_load_dwordx4 v[12:15], v[54:55], off
	global_load_dwordx4 v[16:19], v[56:57], off
	global_load_dwordx4 v[20:23], v[58:59], off
	global_load_dwordx4 v[24:27], v[60:61], off
	global_load_dwordx4 v[28:31], v[62:63], off
	s_waitcnt vmcnt(11)
	v_lshlrev_b32_e32 v64, 16, v44
	v_and_b32_e32 v65, 0xffff0000, v44
	v_lshlrev_b32_e32 v66, 16, v45
	v_and_b32_e32 v67, 0xffff0000, v45
	v_lshlrev_b32_e32 v68, 16, v46
	v_and_b32_e32 v69, 0xffff0000, v46
	v_lshlrev_b32_e32 v70, 16, v47
	v_and_b32_e32 v71, 0xffff0000, v47
	v_lshlrev_b32_e32 v72, 16, v40
	v_and_b32_e32 v73, 0xffff0000, v40
	v_lshlrev_b32_e32 v74, 16, v41
	v_and_b32_e32 v75, 0xffff0000, v41
	v_lshlrev_b32_e32 v76, 16, v42
	v_and_b32_e32 v77, 0xffff0000, v42
	v_lshlrev_b32_e32 v78, 16, v43
	v_and_b32_e32 v79, 0xffff0000, v43
	v_lshlrev_b32_e32 v80, 16, v36
	v_and_b32_e32 v81, 0xffff0000, v36
	v_lshlrev_b32_e32 v82, 16, v37
	v_and_b32_e32 v83, 0xffff0000, v37
	v_lshlrev_b32_e32 v84, 16, v38
	v_and_b32_e32 v85, 0xffff0000, v38
	v_lshlrev_b32_e32 v86, 16, v39
	v_and_b32_e32 v87, 0xffff0000, v39
	v_and_b32_e32 v89, 0xffff0000, v32
	v_lshlrev_b32_e32 v90, 16, v33
	v_and_b32_e32 v91, 0xffff0000, v33
	v_lshlrev_b32_e32 v92, 16, v34
	v_and_b32_e32 v93, 0xffff0000, v34
	v_lshlrev_b32_e32 v94, 16, v35
	v_and_b32_e32 v95, 0xffff0000, v35
